# LN row passes: xor-butterfly wave sums via DPP quad_perm/row_mirror/row_bcast + readlane (bit-exact) instead of 6 ds_bpermute hops
# baseline (speedup 1.0000x reference)
.LBB0_748:
	v_lshl_add_u64 v[120:121], s[30:31], 0, v[82:83]
	v_add_co_u32_e32 v16, vcc, 0x17000000, v120
	s_nop 1
	v_addc_co_u32_e32 v17, vcc, 0, v121, vcc
	global_load_dwordx4 v[0:3], v[16:17], off offset:1024
	global_load_dwordx4 v[4:7], v[16:17], off offset:2048
	global_load_dwordx4 v[8:11], v[16:17], off offset:3072
	global_load_dwordx4 v[12:15], v[16:17], off
	s_waitcnt vmcnt(0)
	v_lshlrev_b32_e32 v114, 16, v2
	v_and_b32_e32 v115, 0xffff0000, v2
	v_lshlrev_b32_e32 v118, 16, v3
	v_lshlrev_b32_e32 v125, 16, v12
	v_lshlrev_b32_e32 v124, 16, v14
	v_and_b32_e32 v129, 0xffff0000, v12
	v_and_b32_e32 v128, 0xffff0000, v14
	v_lshlrev_b32_e32 v131, 16, v13
	v_lshlrev_b32_e32 v130, 16, v15
	v_and_b32_e32 v133, 0xffff0000, v13
	v_and_b32_e32 v132, 0xffff0000, v15
	v_and_b32_e32 v119, 0xffff0000, v3
	v_lshlrev_b32_e32 v123, 16, v1
	v_lshlrev_b32_e32 v122, 16, v0
	v_and_b32_e32 v127, 0xffff0000, v1
	v_and_b32_e32 v126, 0xffff0000, v0
	v_pk_add_f32 v[0:1], v[124:125], v[128:129]
	v_pk_add_f32 v[2:3], v[130:131], v[132:133]
	v_lshlrev_b32_e32 v104, 16, v4
	v_and_b32_e32 v108, 0xffff0000, v4
	v_lshlrev_b32_e32 v106, 16, v5
	v_and_b32_e32 v110, 0xffff0000, v5
	v_pk_add_f32 v[4:5], v[122:123], v[126:127]
	v_pk_add_f32 v[0:1], v[0:1], v[2:3]
	v_pk_add_f32 v[2:3], v[4:5], v[4:5] op_sel_hi:[0,1]
	v_add_f32_e32 v1, 0, v1
	v_add_f32_e32 v105, v114, v115
	v_add_f32_e32 v109, v118, v119
	v_mov_b32_e32 v107, v3
	v_add_f32_e32 v111, v0, v1
	v_lshlrev_b32_e32 v113, 16, v7
	v_lshlrev_b32_e32 v112, 16, v6
	v_and_b32_e32 v117, 0xffff0000, v7
	v_and_b32_e32 v116, 0xffff0000, v6
	v_pk_add_f32 v[4:5], v[104:105], v[108:109]
	v_pk_add_f32 v[0:1], v[106:107], v[110:111]
	v_pk_add_f32 v[6:7], v[112:113], v[116:117]
	v_pk_add_f32 v[0:1], v[4:5], v[0:1]
	v_lshlrev_b32_e32 v100, 16, v8
	v_and_b32_e32 v101, 0xffff0000, v8
	v_lshlrev_b32_e32 v102, 16, v9
	v_and_b32_e32 v103, 0xffff0000, v9
	v_pk_add_f32 v[6:7], v[6:7], v[6:7] op_sel_hi:[0,1]
	v_pk_add_f32 v[0:1], v[0:1], v[0:1] op_sel_hi:[0,1]
	v_lshlrev_b32_e32 v92, 16, v10
	v_and_b32_e32 v96, 0xffff0000, v10
	v_lshlrev_b32_e32 v94, 16, v11
	v_and_b32_e32 v98, 0xffff0000, v11
	v_add_f32_e32 v93, v100, v101
	v_add_f32_e32 v97, v102, v103
	v_mov_b32_e32 v95, v7
	v_mov_b32_e32 v99, v1
	v_pk_add_f32 v[8:9], v[92:93], v[96:97]
	v_pk_add_f32 v[0:1], v[94:95], v[98:99]
	s_nop 0
	v_pk_add_f32 v[0:1], v[8:9], v[0:1]
	s_nop 0
	v_add_f32_e32 v0, v0, v1
	s_nop 1
	v_add_f32_dpp v0, v0, v0 quad_perm:[1,0,3,2] row_mask:0xf bank_mask:0xf
	s_nop 1
	v_add_f32_dpp v0, v0, v0 quad_perm:[2,3,0,1] row_mask:0xf bank_mask:0xf
	s_nop 1
	v_add_f32_dpp v0, v0, v0 row_half_mirror row_mask:0xf bank_mask:0xf
	s_nop 1
	v_add_f32_dpp v0, v0, v0 row_mirror row_mask:0xf bank_mask:0xf
	s_nop 1
	v_add_f32_dpp v0, v0, v0 row_bcast:15 row_mask:0xa bank_mask:0xf
	s_nop 0
	v_readlane_b32 s86, v0, 31
	v_readlane_b32 s87, v0, 63
	s_nop 1
	v_mov_b32_e32 v85, s86
	v_add_f32_e32 v85, s87, v85
	v_fmac_f32_e32 v133, 0xba000000, v85
	v_fmac_f32_e32 v129, 0xba000000, v85
	v_fmac_f32_e32 v132, 0xba000000, v85
	v_fmac_f32_e32 v128, 0xba000000, v85
	v_fmac_f32_e32 v127, 0xba000000, v85
	v_fmac_f32_e32 v123, 0xba000000, v85
	v_fmac_f32_e32 v126, 0xba000000, v85
	v_fmac_f32_e32 v131, 0xba000000, v85
	v_fmac_f32_e32 v125, 0xba000000, v85
	v_fmac_f32_e32 v130, 0xba000000, v85
	v_fmac_f32_e32 v124, 0xba000000, v85
	v_fmac_f32_e32 v122, 0xba000000, v85
	v_mov_b32_e32 v2, v129
	v_mov_b32_e32 v3, v128
	v_mov_b32_e32 v6, v133
	v_mov_b32_e32 v7, v132
	v_mov_b32_e32 v136, v123
	v_mov_b32_e32 v137, v127
	v_mov_b32_e32 v123, v126
	v_mov_b32_e32 v0, v125
	v_mov_b32_e32 v1, v124
	v_mov_b32_e32 v4, v131
	v_mov_b32_e32 v5, v130
	v_pk_mul_f32 v[2:3], v[2:3], v[2:3]
	v_pk_mul_f32 v[6:7], v[6:7], v[6:7]
	v_pk_mul_f32 v[12:13], v[136:137], v[136:137]
	v_pk_mul_f32 v[14:15], v[122:123], v[122:123]
	v_fmac_f32_e32 v118, 0xba000000, v85
	v_fmac_f32_e32 v114, 0xba000000, v85
	v_pk_fma_f32 v[0:1], v[0:1], v[0:1], v[2:3]
	v_pk_fma_f32 v[2:3], v[4:5], v[4:5], v[6:7]
	v_pk_mov_b32 v[4:5], v[14:15], v[12:13] op_sel:[1,0]
	v_mov_b32_e32 v15, v13
	v_fmac_f32_e32 v119, 0xba000000, v85
	v_fmac_f32_e32 v115, 0xba000000, v85
	v_mul_f32_e32 v8, v114, v114
	v_mul_f32_e32 v10, v118, v118
	v_pk_add_f32 v[0:1], v[0:1], v[2:3]
	v_pk_add_f32 v[2:3], v[4:5], v[14:15]
	v_fmac_f32_e32 v110, 0xba000000, v85
	v_fmac_f32_e32 v106, 0xba000000, v85
	v_fmac_f32_e32 v108, 0xba000000, v85
	v_fmac_f32_e32 v104, 0xba000000, v85
	v_pk_fma_f32 v[8:9], v[114:115], v[114:115], v[8:9] op_sel_hi:[1,1,0]
	v_pk_fma_f32 v[10:11], v[118:119], v[118:119], v[10:11] op_sel_hi:[1,1,0]
	v_pk_add_f32 v[0:1], v[0:1], v[0:1] op_sel_hi:[0,1]
	v_pk_add_f32 v[2:3], v[2:3], v[2:3] op_sel_hi:[0,1]
	v_mul_f32_e32 v8, v104, v104
	v_mul_f32_e32 v10, v108, v108
	v_mul_f32_e32 v2, v106, v106
	v_mul_f32_e32 v0, v110, v110
	v_fmac_f32_e32 v117, 0xba000000, v85
	v_fmac_f32_e32 v113, 0xba000000, v85
	v_fmac_f32_e32 v116, 0xba000000, v85
	v_pk_add_f32 v[4:5], v[8:9], v[10:11]
	v_pk_add_f32 v[0:1], v[2:3], v[0:1]
	v_fmac_f32_e32 v112, 0xba000000, v85
	v_mov_b32_e32 v134, v113
	v_mov_b32_e32 v135, v117
	v_mov_b32_e32 v113, v116
	v_pk_add_f32 v[0:1], v[4:5], v[0:1]
	v_pk_mul_f32 v[16:17], v[134:135], v[134:135]
	v_pk_add_f32 v[150:151], v[0:1], v[0:1] op_sel_hi:[0,1]
	v_pk_mul_f32 v[0:1], v[112:113], v[112:113]
	v_fmac_f32_e32 v100, 0xba000000, v85
	v_pk_mov_b32 v[2:3], v[0:1], v[16:17] op_sel:[1,0]
	v_mov_b32_e32 v1, v17
	v_pk_add_f32 v[0:1], v[2:3], v[0:1]
	v_fmac_f32_e32 v102, 0xba000000, v85
	v_pk_add_f32 v[152:153], v[0:1], v[0:1] op_sel_hi:[0,1]
	v_fmac_f32_e32 v101, 0xba000000, v85
	v_mul_f32_e32 v0, v100, v100
	v_fmac_f32_e32 v103, 0xba000000, v85
	v_pk_fma_f32 v[154:155], v[100:101], v[100:101], v[0:1] op_sel_hi:[1,1,0]
	v_mul_f32_e32 v0, v102, v102
	v_pk_fma_f32 v[156:157], v[102:103], v[102:103], v[0:1] op_sel_hi:[1,1,0]
	global_load_dwordx4 v[48:51], v[68:69], off offset:16
	global_load_dwordx4 v[56:59], v[68:69], off
	global_load_dwordx4 v[52:55], v[70:71], off offset:16
	global_load_dwordx4 v[60:63], v[70:71], off
	global_load_dwordx4 v[32:35], v[68:69], off offset:2064
	global_load_dwordx4 v[40:43], v[68:69], off offset:2048
	global_load_dwordx4 v[36:39], v[70:71], off offset:2064
	global_load_dwordx4 v[44:47], v[70:71], off offset:2048
	global_load_dwordx4 v[16:19], v[72:73], off offset:16
	global_load_dwordx4 v[24:27], v[72:73], off
	global_load_dwordx4 v[20:23], v[74:75], off offset:16
	global_load_dwordx4 v[28:31], v[74:75], off
	global_load_dwordx4 v[0:3], v[76:77], off offset:16
	global_load_dwordx4 v[8:11], v[76:77], off
	global_load_dwordx4 v[4:7], v[78:79], off offset:16
	global_load_dwordx4 v[12:15], v[78:79], off
	v_fmac_f32_e32 v98, 0xba000000, v85
	v_fmac_f32_e32 v94, 0xba000000, v85
	v_fmac_f32_e32 v96, 0xba000000, v85
	v_fmac_f32_e32 v92, 0xba000000, v85
	v_mul_f32_e32 v154, v92, v92
	v_mul_f32_e32 v156, v96, v96
	v_mul_f32_e32 v152, v94, v94
	v_mul_f32_e32 v150, v98, v98
	v_pk_add_f32 v[154:155], v[154:155], v[156:157]
	v_pk_add_f32 v[150:151], v[152:153], v[150:151]
	s_nop 0
	v_pk_add_f32 v[150:151], v[154:155], v[150:151]
	s_nop 0
	v_add_f32_e32 v87, v150, v151
	s_nop 1
	v_add_f32_dpp v87, v87, v87 quad_perm:[1,0,3,2] row_mask:0xf bank_mask:0xf
	s_nop 1
	v_add_f32_dpp v87, v87, v87 quad_perm:[2,3,0,1] row_mask:0xf bank_mask:0xf
	s_nop 1
	v_add_f32_dpp v87, v87, v87 row_half_mirror row_mask:0xf bank_mask:0xf
	s_nop 1
	v_add_f32_dpp v87, v87, v87 row_mirror row_mask:0xf bank_mask:0xf
	s_nop 1
	v_add_f32_dpp v87, v87, v87 row_bcast:15 row_mask:0xa bank_mask:0xf
	s_nop 0
	v_readlane_b32 s86, v87, 31
	v_readlane_b32 s87, v87, 63
	s_nop 1
	v_mov_b32_e32 v87, s86
	v_add_f32_e32 v87, s87, v87
	v_fmamk_f32 v87, v87, 0x3a000000, v65
	v_mul_f32_e32 v89, 0x4f800000, v87
	v_cmp_gt_f32_e32 vcc, s3, v87
	s_nop 1
	v_cndmask_b32_e32 v87, v87, v89, vcc
	v_sqrt_f32_e32 v89, v87
	s_nop 0
	v_add_u32_e32 v91, -1, v89
	v_fma_f32 v93, -v91, v89, v87
	v_cmp_ge_f32_e64 s[4:5], 0, v93
	v_add_u32_e32 v93, 1, v89
	s_nop 0
	v_cndmask_b32_e64 v91, v89, v91, s[4:5]
	v_fma_f32 v89, -v93, v89, v87
	v_cmp_lt_f32_e64 s[4:5], 0, v89
	s_nop 1
	v_cndmask_b32_e64 v89, v91, v93, s[4:5]
	v_mul_f32_e32 v91, 0x37800000, v89
	v_cndmask_b32_e32 v89, v89, v91, vcc
	v_cmp_class_f32_e32 vcc, v87, v149
	s_nop 1
	v_cndmask_b32_e32 v87, v89, v87, vcc
	v_div_scale_f32 v89, s[4:5], v87, v87, 1.0
	v_rcp_f32_e32 v91, v89
	s_nop 0
	v_fma_f32 v93, -v89, v91, 1.0
	v_fmac_f32_e32 v91, v93, v91
	v_div_scale_f32 v93, vcc, 1.0, v87, 1.0
	v_mul_f32_e32 v95, v93, v91
	v_fma_f32 v97, -v89, v95, v93
	v_fmac_f32_e32 v95, v97, v91
	v_fma_f32 v89, -v89, v95, v93
	v_div_fmas_f32 v89, v89, v91, v95
	v_div_fixup_f32 v138, v89, v87, 1.0
	s_and_saveexec_b64 s[4:5], s[0:1]
	s_cbranch_execz .LBB0_747
	v_mul_f32_e32 v150, 0x3a000000, v85
	v_lshl_add_u64 v[152:153], s[30:31], 0, v[80:81]
	v_mov_b32_e32 v151, v138
	global_store_dwordx2 v[152:153], v[150:151], off
	s_branch .LBB0_747

.LBB0_947:
	v_lshl_add_u64 v[124:125], s[30:31], 0, v[86:87]
	v_add_co_u32_e32 v16, vcc, 0xf000000, v124
	s_nop 1
	v_addc_co_u32_e32 v17, vcc, 0, v125, vcc
	global_load_dwordx4 v[0:3], v[16:17], off offset:1024
	global_load_dwordx4 v[4:7], v[16:17], off offset:2048
	global_load_dwordx4 v[8:11], v[16:17], off offset:3072
	global_load_dwordx4 v[12:15], v[16:17], off
	s_waitcnt vmcnt(0)
	v_lshlrev_b32_e32 v118, 16, v2
	v_and_b32_e32 v119, 0xffff0000, v2
	v_lshlrev_b32_e32 v122, 16, v3
	v_lshlrev_b32_e32 v129, 16, v12
	v_lshlrev_b32_e32 v128, 16, v14
	v_and_b32_e32 v133, 0xffff0000, v12
	v_and_b32_e32 v132, 0xffff0000, v14
	v_lshlrev_b32_e32 v135, 16, v13
	v_lshlrev_b32_e32 v134, 16, v15
	v_and_b32_e32 v137, 0xffff0000, v13
	v_and_b32_e32 v136, 0xffff0000, v15
	v_and_b32_e32 v123, 0xffff0000, v3
	v_lshlrev_b32_e32 v127, 16, v1
	v_lshlrev_b32_e32 v126, 16, v0
	v_and_b32_e32 v131, 0xffff0000, v1
	v_and_b32_e32 v130, 0xffff0000, v0
	v_pk_add_f32 v[0:1], v[128:129], v[132:133]
	v_pk_add_f32 v[2:3], v[134:135], v[136:137]
	v_lshlrev_b32_e32 v108, 16, v4
	v_and_b32_e32 v112, 0xffff0000, v4
	v_lshlrev_b32_e32 v110, 16, v5
	v_and_b32_e32 v114, 0xffff0000, v5
	v_pk_add_f32 v[4:5], v[126:127], v[130:131]
	v_pk_add_f32 v[0:1], v[0:1], v[2:3]
	v_pk_add_f32 v[2:3], v[4:5], v[4:5] op_sel_hi:[0,1]
	v_add_f32_e32 v1, 0, v1
	v_add_f32_e32 v109, v118, v119
	v_add_f32_e32 v113, v122, v123
	v_mov_b32_e32 v111, v3
	v_add_f32_e32 v115, v0, v1
	v_lshlrev_b32_e32 v117, 16, v7
	v_lshlrev_b32_e32 v116, 16, v6
	v_and_b32_e32 v121, 0xffff0000, v7
	v_and_b32_e32 v120, 0xffff0000, v6
	v_pk_add_f32 v[4:5], v[108:109], v[112:113]
	v_pk_add_f32 v[0:1], v[110:111], v[114:115]
	v_pk_add_f32 v[6:7], v[116:117], v[120:121]
	v_pk_add_f32 v[0:1], v[4:5], v[0:1]
	v_lshlrev_b32_e32 v104, 16, v8
	v_and_b32_e32 v105, 0xffff0000, v8
	v_lshlrev_b32_e32 v106, 16, v9
	v_and_b32_e32 v107, 0xffff0000, v9
	v_pk_add_f32 v[6:7], v[6:7], v[6:7] op_sel_hi:[0,1]
	v_pk_add_f32 v[0:1], v[0:1], v[0:1] op_sel_hi:[0,1]
	v_lshlrev_b32_e32 v96, 16, v10
	v_and_b32_e32 v100, 0xffff0000, v10
	v_lshlrev_b32_e32 v98, 16, v11
	v_and_b32_e32 v102, 0xffff0000, v11
	v_add_f32_e32 v97, v104, v105
	v_add_f32_e32 v101, v106, v107
	v_mov_b32_e32 v99, v7
	v_mov_b32_e32 v103, v1
	v_pk_add_f32 v[8:9], v[96:97], v[100:101]
	v_pk_add_f32 v[0:1], v[98:99], v[102:103]
	s_nop 0
	v_pk_add_f32 v[0:1], v[8:9], v[0:1]
	s_nop 0
	v_add_f32_e32 v0, v0, v1
	s_nop 1
	v_add_f32_dpp v0, v0, v0 quad_perm:[1,0,3,2] row_mask:0xf bank_mask:0xf
	s_nop 1
	v_add_f32_dpp v0, v0, v0 quad_perm:[2,3,0,1] row_mask:0xf bank_mask:0xf
	s_nop 1
	v_add_f32_dpp v0, v0, v0 row_half_mirror row_mask:0xf bank_mask:0xf
	s_nop 1
	v_add_f32_dpp v0, v0, v0 row_mirror row_mask:0xf bank_mask:0xf
	s_nop 1
	v_add_f32_dpp v0, v0, v0 row_bcast:15 row_mask:0xa bank_mask:0xf
	s_nop 0
	v_readlane_b32 s86, v0, 31
	v_readlane_b32 s87, v0, 63
	s_nop 1
	v_mov_b32_e32 v89, s86
	v_add_f32_e32 v89, s87, v89
	v_fmac_f32_e32 v137, 0xba000000, v89
	v_fmac_f32_e32 v133, 0xba000000, v89
	v_fmac_f32_e32 v136, 0xba000000, v89
	v_fmac_f32_e32 v132, 0xba000000, v89
	v_fmac_f32_e32 v131, 0xba000000, v89
	v_fmac_f32_e32 v127, 0xba000000, v89
	v_fmac_f32_e32 v130, 0xba000000, v89
	v_fmac_f32_e32 v135, 0xba000000, v89
	v_fmac_f32_e32 v129, 0xba000000, v89
	v_fmac_f32_e32 v134, 0xba000000, v89
	v_fmac_f32_e32 v128, 0xba000000, v89
	v_fmac_f32_e32 v126, 0xba000000, v89
	v_mov_b32_e32 v2, v133
	v_mov_b32_e32 v3, v132
	v_mov_b32_e32 v6, v137
	v_mov_b32_e32 v7, v136
	v_mov_b32_e32 v140, v127
	v_mov_b32_e32 v141, v131
	v_mov_b32_e32 v127, v130
	v_mov_b32_e32 v0, v129
	v_mov_b32_e32 v1, v128
	v_mov_b32_e32 v4, v135
	v_mov_b32_e32 v5, v134
	v_pk_mul_f32 v[2:3], v[2:3], v[2:3]
	v_pk_mul_f32 v[6:7], v[6:7], v[6:7]
	v_pk_mul_f32 v[12:13], v[140:141], v[140:141]
	v_pk_mul_f32 v[14:15], v[126:127], v[126:127]
	v_fmac_f32_e32 v122, 0xba000000, v89
	v_fmac_f32_e32 v118, 0xba000000, v89
	v_pk_fma_f32 v[0:1], v[0:1], v[0:1], v[2:3]
	v_pk_fma_f32 v[2:3], v[4:5], v[4:5], v[6:7]
	v_pk_mov_b32 v[4:5], v[14:15], v[12:13] op_sel:[1,0]
	v_mov_b32_e32 v15, v13
	v_fmac_f32_e32 v123, 0xba000000, v89
	v_fmac_f32_e32 v119, 0xba000000, v89
	v_mul_f32_e32 v8, v118, v118
	v_mul_f32_e32 v10, v122, v122
	v_pk_add_f32 v[0:1], v[0:1], v[2:3]
	v_pk_add_f32 v[2:3], v[4:5], v[14:15]
	v_fmac_f32_e32 v114, 0xba000000, v89
	v_fmac_f32_e32 v110, 0xba000000, v89
	v_fmac_f32_e32 v112, 0xba000000, v89
	v_fmac_f32_e32 v108, 0xba000000, v89
	v_pk_fma_f32 v[8:9], v[118:119], v[118:119], v[8:9] op_sel_hi:[1,1,0]
	v_pk_fma_f32 v[10:11], v[122:123], v[122:123], v[10:11] op_sel_hi:[1,1,0]
	v_pk_add_f32 v[0:1], v[0:1], v[0:1] op_sel_hi:[0,1]
	v_pk_add_f32 v[2:3], v[2:3], v[2:3] op_sel_hi:[0,1]
	v_mul_f32_e32 v8, v108, v108
	v_mul_f32_e32 v10, v112, v112
	v_mul_f32_e32 v2, v110, v110
	v_mul_f32_e32 v0, v114, v114
	v_fmac_f32_e32 v121, 0xba000000, v89
	v_fmac_f32_e32 v117, 0xba000000, v89
	v_fmac_f32_e32 v120, 0xba000000, v89
	v_pk_add_f32 v[4:5], v[8:9], v[10:11]
	v_pk_add_f32 v[0:1], v[2:3], v[0:1]
	v_fmac_f32_e32 v116, 0xba000000, v89
	v_mov_b32_e32 v138, v117
	v_mov_b32_e32 v139, v121
	v_mov_b32_e32 v117, v120
	v_pk_add_f32 v[0:1], v[4:5], v[0:1]
	v_pk_mul_f32 v[16:17], v[138:139], v[138:139]
	v_pk_add_f32 v[154:155], v[0:1], v[0:1] op_sel_hi:[0,1]
	v_pk_mul_f32 v[0:1], v[116:117], v[116:117]
	v_fmac_f32_e32 v104, 0xba000000, v89
	v_pk_mov_b32 v[2:3], v[0:1], v[16:17] op_sel:[1,0]
	v_mov_b32_e32 v1, v17
	v_pk_add_f32 v[0:1], v[2:3], v[0:1]
	v_fmac_f32_e32 v106, 0xba000000, v89
	v_pk_add_f32 v[156:157], v[0:1], v[0:1] op_sel_hi:[0,1]
	v_fmac_f32_e32 v105, 0xba000000, v89
	v_mul_f32_e32 v0, v104, v104
	v_fmac_f32_e32 v107, 0xba000000, v89
	v_pk_fma_f32 v[158:159], v[104:105], v[104:105], v[0:1] op_sel_hi:[1,1,0]
	v_mul_f32_e32 v0, v106, v106
	v_pk_fma_f32 v[160:161], v[106:107], v[106:107], v[0:1] op_sel_hi:[1,1,0]
	global_load_dwordx4 v[48:51], v[68:69], off offset:16
	global_load_dwordx4 v[56:59], v[68:69], off
	global_load_dwordx4 v[52:55], v[70:71], off offset:16
	global_load_dwordx4 v[60:63], v[70:71], off
	global_load_dwordx4 v[32:35], v[72:73], off offset:16
	global_load_dwordx4 v[40:43], v[72:73], off
	global_load_dwordx4 v[36:39], v[74:75], off offset:16
	global_load_dwordx4 v[44:47], v[74:75], off
	global_load_dwordx4 v[16:19], v[76:77], off offset:16
	global_load_dwordx4 v[24:27], v[76:77], off
	global_load_dwordx4 v[20:23], v[78:79], off offset:16
	global_load_dwordx4 v[28:31], v[78:79], off
	global_load_dwordx4 v[0:3], v[80:81], off offset:16
	global_load_dwordx4 v[8:11], v[80:81], off
	global_load_dwordx4 v[4:7], v[82:83], off offset:16
	global_load_dwordx4 v[12:15], v[82:83], off
	v_fmac_f32_e32 v102, 0xba000000, v89
	v_fmac_f32_e32 v98, 0xba000000, v89
	v_fmac_f32_e32 v100, 0xba000000, v89
	v_fmac_f32_e32 v96, 0xba000000, v89
	v_mul_f32_e32 v158, v96, v96
	v_mul_f32_e32 v160, v100, v100
	v_mul_f32_e32 v156, v98, v98
	v_mul_f32_e32 v154, v102, v102
	v_pk_add_f32 v[158:159], v[158:159], v[160:161]
	v_pk_add_f32 v[154:155], v[156:157], v[154:155]
	s_nop 0
	v_pk_add_f32 v[154:155], v[158:159], v[154:155]
	s_nop 0
	v_add_f32_e32 v91, v154, v155
	s_nop 1
	v_add_f32_dpp v91, v91, v91 quad_perm:[1,0,3,2] row_mask:0xf bank_mask:0xf
	s_nop 1
	v_add_f32_dpp v91, v91, v91 quad_perm:[2,3,0,1] row_mask:0xf bank_mask:0xf
	s_nop 1
	v_add_f32_dpp v91, v91, v91 row_half_mirror row_mask:0xf bank_mask:0xf
	s_nop 1
	v_add_f32_dpp v91, v91, v91 row_mirror row_mask:0xf bank_mask:0xf
	s_nop 1
	v_add_f32_dpp v91, v91, v91 row_bcast:15 row_mask:0xa bank_mask:0xf
	s_nop 0
	v_readlane_b32 s86, v91, 31
	v_readlane_b32 s87, v91, 63
	s_nop 1
	v_mov_b32_e32 v91, s86
	v_add_f32_e32 v91, s87, v91
	v_fmamk_f32 v91, v91, 0x3a000000, v65
	v_mul_f32_e32 v93, 0x4f800000, v91
	v_cmp_gt_f32_e32 vcc, s3, v91
	s_nop 1
	v_cndmask_b32_e32 v91, v91, v93, vcc
	v_sqrt_f32_e32 v93, v91
	s_nop 0
	v_add_u32_e32 v95, -1, v93
	v_fma_f32 v97, -v95, v93, v91
	v_cmp_ge_f32_e64 s[4:5], 0, v97
	v_add_u32_e32 v97, 1, v93
	s_nop 0
	v_cndmask_b32_e64 v95, v93, v95, s[4:5]
	v_fma_f32 v93, -v97, v93, v91
	v_cmp_lt_f32_e64 s[4:5], 0, v93
	s_nop 1
	v_cndmask_b32_e64 v93, v95, v97, s[4:5]
	v_mul_f32_e32 v95, 0x37800000, v93
	v_cndmask_b32_e32 v93, v93, v95, vcc
	v_cmp_class_f32_e32 vcc, v91, v153
	s_nop 1
	v_cndmask_b32_e32 v91, v93, v91, vcc
	v_div_scale_f32 v93, s[4:5], v91, v91, 1.0
	v_rcp_f32_e32 v95, v93
	s_nop 0
	v_fma_f32 v97, -v93, v95, 1.0
	v_fmac_f32_e32 v95, v97, v95
	v_div_scale_f32 v97, vcc, 1.0, v91, 1.0
	v_mul_f32_e32 v99, v97, v95
	v_fma_f32 v101, -v93, v99, v97
	v_fmac_f32_e32 v99, v101, v95
	v_fma_f32 v93, -v93, v99, v97
	v_div_fmas_f32 v93, v93, v95, v99
	v_div_fixup_f32 v142, v93, v91, 1.0
	s_and_saveexec_b64 s[4:5], s[0:1]
	s_cbranch_execz .LBB0_946
	v_mul_f32_e32 v154, 0x3a000000, v89
	v_lshl_add_u64 v[156:157], s[30:31], 0, v[84:85]
	v_mov_b32_e32 v155, v142
	global_store_dwordx2 v[156:157], v[154:155], off
	s_branch .LBB0_946

.LBB0_2483:
	s_waitcnt vmcnt(0)
	v_lshl_add_u64 v[124:125], s[30:31], 0, v[86:87]
	v_add_co_u32_e32 v16, vcc, 0x17000000, v124
	s_nop 1
	v_addc_co_u32_e32 v17, vcc, 0, v125, vcc
	global_load_dwordx4 v[0:3], v[16:17], off offset:1024
	global_load_dwordx4 v[4:7], v[16:17], off offset:2048
	global_load_dwordx4 v[8:11], v[16:17], off offset:3072
	global_load_dwordx4 v[12:15], v[16:17], off
	s_waitcnt vmcnt(3)
	v_lshlrev_b32_e32 v118, 16, v2
	v_and_b32_e32 v119, 0xffff0000, v2
	v_lshlrev_b32_e32 v122, 16, v3
	s_waitcnt vmcnt(0)
	v_lshlrev_b32_e32 v129, 16, v12
	v_lshlrev_b32_e32 v128, 16, v14
	v_and_b32_e32 v133, 0xffff0000, v12
	v_and_b32_e32 v132, 0xffff0000, v14
	v_lshlrev_b32_e32 v135, 16, v13
	v_lshlrev_b32_e32 v134, 16, v15
	v_and_b32_e32 v137, 0xffff0000, v13
	v_and_b32_e32 v136, 0xffff0000, v15
	v_and_b32_e32 v123, 0xffff0000, v3
	v_lshlrev_b32_e32 v127, 16, v1
	v_lshlrev_b32_e32 v126, 16, v0
	v_and_b32_e32 v131, 0xffff0000, v1
	v_and_b32_e32 v130, 0xffff0000, v0
	v_pk_add_f32 v[0:1], v[128:129], v[132:133]
	v_pk_add_f32 v[2:3], v[134:135], v[136:137]
	v_lshlrev_b32_e32 v108, 16, v4
	v_and_b32_e32 v112, 0xffff0000, v4
	v_lshlrev_b32_e32 v110, 16, v5
	v_and_b32_e32 v114, 0xffff0000, v5
	v_pk_add_f32 v[4:5], v[126:127], v[130:131]
	v_pk_add_f32 v[0:1], v[0:1], v[2:3]
	v_pk_add_f32 v[2:3], v[4:5], v[4:5] op_sel_hi:[0,1]
	v_add_f32_e32 v1, 0, v1
	v_add_f32_e32 v109, v118, v119
	v_add_f32_e32 v113, v122, v123
	v_mov_b32_e32 v111, v3
	v_add_f32_e32 v115, v0, v1
	v_lshlrev_b32_e32 v117, 16, v7
	v_lshlrev_b32_e32 v116, 16, v6
	v_and_b32_e32 v121, 0xffff0000, v7
	v_and_b32_e32 v120, 0xffff0000, v6
	v_pk_add_f32 v[4:5], v[108:109], v[112:113]
	v_pk_add_f32 v[0:1], v[110:111], v[114:115]
	v_pk_add_f32 v[6:7], v[116:117], v[120:121]
	v_pk_add_f32 v[0:1], v[4:5], v[0:1]
	v_lshlrev_b32_e32 v104, 16, v8
	v_and_b32_e32 v105, 0xffff0000, v8
	v_lshlrev_b32_e32 v106, 16, v9
	v_and_b32_e32 v107, 0xffff0000, v9
	v_pk_add_f32 v[6:7], v[6:7], v[6:7] op_sel_hi:[0,1]
	v_pk_add_f32 v[0:1], v[0:1], v[0:1] op_sel_hi:[0,1]
	v_lshlrev_b32_e32 v96, 16, v10
	v_and_b32_e32 v100, 0xffff0000, v10
	v_lshlrev_b32_e32 v98, 16, v11
	v_and_b32_e32 v102, 0xffff0000, v11
	v_add_f32_e32 v97, v104, v105
	v_add_f32_e32 v101, v106, v107
	v_mov_b32_e32 v99, v7
	v_mov_b32_e32 v103, v1
	v_pk_add_f32 v[8:9], v[96:97], v[100:101]
	v_pk_add_f32 v[0:1], v[98:99], v[102:103]
	s_nop 0
	v_pk_add_f32 v[0:1], v[8:9], v[0:1]
	s_nop 0
	v_add_f32_e32 v0, v0, v1
	s_nop 1
	v_add_f32_dpp v0, v0, v0 quad_perm:[1,0,3,2] row_mask:0xf bank_mask:0xf
	s_nop 1
	v_add_f32_dpp v0, v0, v0 quad_perm:[2,3,0,1] row_mask:0xf bank_mask:0xf
	s_nop 1
	v_add_f32_dpp v0, v0, v0 row_half_mirror row_mask:0xf bank_mask:0xf
	s_nop 1
	v_add_f32_dpp v0, v0, v0 row_mirror row_mask:0xf bank_mask:0xf
	s_nop 1
	v_add_f32_dpp v0, v0, v0 row_bcast:15 row_mask:0xa bank_mask:0xf
	s_nop 0
	v_readlane_b32 s86, v0, 31
	v_readlane_b32 s87, v0, 63
	s_nop 1
	v_mov_b32_e32 v89, s86
	v_add_f32_e32 v89, s87, v89
	v_fmac_f32_e32 v137, 0xba000000, v89
	v_fmac_f32_e32 v133, 0xba000000, v89
	v_fmac_f32_e32 v136, 0xba000000, v89
	v_fmac_f32_e32 v132, 0xba000000, v89
	v_fmac_f32_e32 v131, 0xba000000, v89
	v_fmac_f32_e32 v127, 0xba000000, v89
	v_fmac_f32_e32 v130, 0xba000000, v89
	v_fmac_f32_e32 v135, 0xba000000, v89
	v_fmac_f32_e32 v129, 0xba000000, v89
	v_fmac_f32_e32 v134, 0xba000000, v89
	v_fmac_f32_e32 v128, 0xba000000, v89
	v_fmac_f32_e32 v126, 0xba000000, v89
	v_mov_b32_e32 v2, v133
	v_mov_b32_e32 v3, v132
	v_mov_b32_e32 v6, v137
	v_mov_b32_e32 v7, v136
	v_mov_b32_e32 v140, v127
	v_mov_b32_e32 v141, v131
	v_mov_b32_e32 v127, v130
	v_mov_b32_e32 v0, v129
	v_mov_b32_e32 v1, v128
	v_mov_b32_e32 v4, v135
	v_mov_b32_e32 v5, v134
	v_pk_mul_f32 v[2:3], v[2:3], v[2:3]
	v_pk_mul_f32 v[6:7], v[6:7], v[6:7]
	v_pk_mul_f32 v[12:13], v[140:141], v[140:141]
	v_pk_mul_f32 v[14:15], v[126:127], v[126:127]
	v_fmac_f32_e32 v122, 0xba000000, v89
	v_fmac_f32_e32 v118, 0xba000000, v89
	v_pk_fma_f32 v[0:1], v[0:1], v[0:1], v[2:3]
	v_pk_fma_f32 v[2:3], v[4:5], v[4:5], v[6:7]
	v_pk_mov_b32 v[4:5], v[14:15], v[12:13] op_sel:[1,0]
	v_mov_b32_e32 v15, v13
	v_fmac_f32_e32 v123, 0xba000000, v89
	v_fmac_f32_e32 v119, 0xba000000, v89
	v_mul_f32_e32 v8, v118, v118
	v_mul_f32_e32 v10, v122, v122
	v_pk_add_f32 v[0:1], v[0:1], v[2:3]
	v_pk_add_f32 v[2:3], v[4:5], v[14:15]
	v_fmac_f32_e32 v114, 0xba000000, v89
	v_fmac_f32_e32 v110, 0xba000000, v89
	v_fmac_f32_e32 v112, 0xba000000, v89
	v_fmac_f32_e32 v108, 0xba000000, v89
	v_pk_fma_f32 v[8:9], v[118:119], v[118:119], v[8:9] op_sel_hi:[1,1,0]
	v_pk_fma_f32 v[10:11], v[122:123], v[122:123], v[10:11] op_sel_hi:[1,1,0]
	v_pk_add_f32 v[0:1], v[0:1], v[0:1] op_sel_hi:[0,1]
	v_pk_add_f32 v[2:3], v[2:3], v[2:3] op_sel_hi:[0,1]
	v_mul_f32_e32 v8, v108, v108
	v_mul_f32_e32 v10, v112, v112
	v_mul_f32_e32 v2, v110, v110
	v_mul_f32_e32 v0, v114, v114
	v_fmac_f32_e32 v121, 0xba000000, v89
	v_fmac_f32_e32 v117, 0xba000000, v89
	v_fmac_f32_e32 v120, 0xba000000, v89
	v_pk_add_f32 v[4:5], v[8:9], v[10:11]
	v_pk_add_f32 v[0:1], v[2:3], v[0:1]
	v_fmac_f32_e32 v116, 0xba000000, v89
	v_mov_b32_e32 v138, v117
	v_mov_b32_e32 v139, v121
	v_mov_b32_e32 v117, v120
	v_pk_add_f32 v[0:1], v[4:5], v[0:1]
	v_pk_mul_f32 v[16:17], v[138:139], v[138:139]
	v_pk_add_f32 v[154:155], v[0:1], v[0:1] op_sel_hi:[0,1]
	v_pk_mul_f32 v[0:1], v[116:117], v[116:117]
	v_fmac_f32_e32 v104, 0xba000000, v89
	v_pk_mov_b32 v[2:3], v[0:1], v[16:17] op_sel:[1,0]
	v_mov_b32_e32 v1, v17
	v_pk_add_f32 v[0:1], v[2:3], v[0:1]
	v_fmac_f32_e32 v106, 0xba000000, v89
	v_pk_add_f32 v[156:157], v[0:1], v[0:1] op_sel_hi:[0,1]
	v_fmac_f32_e32 v105, 0xba000000, v89
	v_mul_f32_e32 v0, v104, v104
	v_fmac_f32_e32 v107, 0xba000000, v89
	v_pk_fma_f32 v[158:159], v[104:105], v[104:105], v[0:1] op_sel_hi:[1,1,0]
	v_mul_f32_e32 v0, v106, v106
	v_pk_fma_f32 v[160:161], v[106:107], v[106:107], v[0:1] op_sel_hi:[1,1,0]
	global_load_dwordx4 v[48:51], v[68:69], off offset:16
	global_load_dwordx4 v[56:59], v[68:69], off
	global_load_dwordx4 v[52:55], v[70:71], off offset:16
	global_load_dwordx4 v[60:63], v[70:71], off
	global_load_dwordx4 v[32:35], v[72:73], off offset:16
	global_load_dwordx4 v[40:43], v[72:73], off
	global_load_dwordx4 v[36:39], v[74:75], off offset:16
	global_load_dwordx4 v[44:47], v[74:75], off
	global_load_dwordx4 v[16:19], v[76:77], off offset:16
	global_load_dwordx4 v[24:27], v[76:77], off
	global_load_dwordx4 v[20:23], v[78:79], off offset:16
	global_load_dwordx4 v[28:31], v[78:79], off
	global_load_dwordx4 v[0:3], v[80:81], off offset:16
	global_load_dwordx4 v[8:11], v[80:81], off
	global_load_dwordx4 v[4:7], v[82:83], off offset:16
	global_load_dwordx4 v[12:15], v[82:83], off
	v_fmac_f32_e32 v102, 0xba000000, v89
	v_fmac_f32_e32 v98, 0xba000000, v89
	v_fmac_f32_e32 v100, 0xba000000, v89
	v_fmac_f32_e32 v96, 0xba000000, v89
	v_mul_f32_e32 v158, v96, v96
	v_mul_f32_e32 v160, v100, v100
	v_mul_f32_e32 v156, v98, v98
	v_mul_f32_e32 v154, v102, v102
	v_pk_add_f32 v[158:159], v[158:159], v[160:161]
	v_pk_add_f32 v[154:155], v[156:157], v[154:155]
	s_nop 0
	v_pk_add_f32 v[154:155], v[158:159], v[154:155]
	s_nop 0
	v_add_f32_e32 v91, v154, v155
	s_nop 1
	v_add_f32_dpp v91, v91, v91 quad_perm:[1,0,3,2] row_mask:0xf bank_mask:0xf
	s_nop 1
	v_add_f32_dpp v91, v91, v91 quad_perm:[2,3,0,1] row_mask:0xf bank_mask:0xf
	s_nop 1
	v_add_f32_dpp v91, v91, v91 row_half_mirror row_mask:0xf bank_mask:0xf
	s_nop 1
	v_add_f32_dpp v91, v91, v91 row_mirror row_mask:0xf bank_mask:0xf
	s_nop 1
	v_add_f32_dpp v91, v91, v91 row_bcast:15 row_mask:0xa bank_mask:0xf
	s_nop 0
	v_readlane_b32 s86, v91, 31
	v_readlane_b32 s87, v91, 63
	s_nop 1
	v_mov_b32_e32 v91, s86
	v_add_f32_e32 v91, s87, v91
	v_fmamk_f32 v91, v91, 0x3a000000, v65
	v_mul_f32_e32 v93, 0x4f800000, v91
	v_cmp_gt_f32_e32 vcc, s3, v91
	s_nop 1
	v_cndmask_b32_e32 v91, v91, v93, vcc
	v_sqrt_f32_e32 v93, v91
	s_nop 0
	v_add_u32_e32 v95, -1, v93
	v_fma_f32 v97, -v95, v93, v91
	v_cmp_ge_f32_e64 s[4:5], 0, v97
	v_add_u32_e32 v97, 1, v93
	s_nop 0
	v_cndmask_b32_e64 v95, v93, v95, s[4:5]
	v_fma_f32 v93, -v97, v93, v91
	v_cmp_lt_f32_e64 s[4:5], 0, v93
	s_nop 1
	v_cndmask_b32_e64 v93, v95, v97, s[4:5]
	v_mul_f32_e32 v95, 0x37800000, v93
	v_cndmask_b32_e32 v93, v93, v95, vcc
	v_cmp_class_f32_e32 vcc, v91, v152
	s_nop 1
	v_cndmask_b32_e32 v91, v93, v91, vcc
	v_div_scale_f32 v93, s[4:5], v91, v91, 1.0
	v_rcp_f32_e32 v95, v93
	s_nop 0
	v_fma_f32 v97, -v93, v95, 1.0
	v_fmac_f32_e32 v95, v97, v95
	v_div_scale_f32 v97, vcc, 1.0, v91, 1.0
	v_mul_f32_e32 v99, v97, v95
	v_fma_f32 v101, -v93, v99, v97
	v_fmac_f32_e32 v99, v101, v95
	v_fma_f32 v93, -v93, v99, v97
	v_div_fmas_f32 v93, v93, v95, v99
	v_div_fixup_f32 v142, v93, v91, 1.0
	s_and_saveexec_b64 s[4:5], s[0:1]
	s_cbranch_execz .LBB0_2482
	v_mul_f32_e32 v154, 0x3a000000, v89
	v_lshl_add_u64 v[156:157], s[30:31], 0, v[84:85]
	v_mov_b32_e32 v155, v142
	global_store_dwordx2 v[156:157], v[154:155], off
	s_branch .LBB0_2482

.LBB0_2681:
	global_load_dwordx4 v[0:3], v[48:49], off offset:1024
	global_load_dwordx4 v[4:7], v[48:49], off offset:2048
	global_load_dwordx4 v[12:15], v[48:49], off offset:3072
	global_load_dwordx4 v[8:11], v[48:49], off
	global_load_dwordx4 v[72:75], v[16:17], off
	global_load_dwordx4 v[76:79], v[18:19], off
	v_add_u32_e32 v148, s2, v148
	v_lshl_add_u64 v[48:49], v[48:49], 0, s[4:5]
	s_waitcnt vmcnt(0)
	global_load_dwordx4 v[170:173], v[20:21], off
	global_load_dwordx4 v[174:177], v[22:23], off
	global_load_dwordx4 v[178:181], v[24:25], off
	global_load_dwordx4 v[182:185], v[26:27], off
	global_load_dwordx4 v[186:189], v[28:29], off
	global_load_dwordx4 v[190:193], v[30:31], off
	global_load_dwordx4 v[194:197], v[32:33], off
	global_load_dwordx4 v[198:201], v[34:35], off
	global_load_dwordx4 v[202:205], v[36:37], off
	global_load_dwordx4 v[206:209], v[38:39], off
	global_load_dwordx4 v[210:213], v[40:41], off
	global_load_dwordx4 v[214:217], v[42:43], off
	global_load_dwordx4 v[218:221], v[44:45], off
	global_load_dwordx4 v[222:225], v[46:47], off
	v_lshlrev_b32_e32 v80, 16, v2
	v_and_b32_e32 v81, 0xffff0000, v2
	v_lshlrev_b32_e32 v52, 16, v12
	v_lshlrev_b32_e32 v85, 16, v8
	v_lshlrev_b32_e32 v84, 16, v10
	v_and_b32_e32 v87, 0xffff0000, v8
	v_and_b32_e32 v86, 0xffff0000, v10
	v_lshlrev_b32_e32 v89, 16, v9
	v_lshlrev_b32_e32 v88, 16, v11
	v_and_b32_e32 v91, 0xffff0000, v9
	v_and_b32_e32 v90, 0xffff0000, v11
	v_and_b32_e32 v53, 0xffff0000, v12
	v_lshlrev_b32_e32 v54, 16, v13
	v_and_b32_e32 v55, 0xffff0000, v13
	v_lshlrev_b32_e32 v11, 16, v1
	v_lshlrev_b32_e32 v10, 16, v0
	v_and_b32_e32 v9, 0xffff0000, v1
	v_and_b32_e32 v8, 0xffff0000, v0
	v_pk_add_f32 v[92:93], v[84:85], v[86:87]
	v_pk_add_f32 v[94:95], v[88:89], v[90:91]
	v_lshlrev_b32_e32 v82, 16, v3
	v_and_b32_e32 v83, 0xffff0000, v3
	v_lshlrev_b32_e32 v2, 16, v14
	v_and_b32_e32 v12, 0xffff0000, v14
	v_pk_add_f32 v[96:97], v[10:11], v[8:9]
	v_add_f32_e32 v3, v52, v53
	v_add_f32_e32 v13, v54, v55
	v_pk_add_f32 v[92:93], v[92:93], v[94:95]
	v_pk_add_f32 v[94:95], v[96:97], v[96:97] op_sel_hi:[0,1]
	v_pk_add_f32 v[100:101], v[2:3], v[12:13]
	v_add_f32_e32 v3, 0, v93
	v_lshlrev_b32_e32 v56, 16, v4
	v_and_b32_e32 v60, 0xffff0000, v4
	v_lshlrev_b32_e32 v58, 16, v5
	v_and_b32_e32 v62, 0xffff0000, v5
	v_add_f32_e32 v57, v80, v81
	v_add_f32_e32 v61, v82, v83
	v_mov_b32_e32 v59, v95
	v_add_f32_e32 v63, v92, v3
	v_lshlrev_b32_e32 v1, 16, v7
	v_lshlrev_b32_e32 v0, 16, v6
	v_and_b32_e32 v7, 0xffff0000, v7
	v_and_b32_e32 v6, 0xffff0000, v6
	v_pk_add_f32 v[96:97], v[56:57], v[60:61]
	v_pk_add_f32 v[92:93], v[58:59], v[62:63]
	v_pk_add_f32 v[98:99], v[0:1], v[6:7]
	v_pk_add_f32 v[92:93], v[96:97], v[92:93]
	v_pk_add_f32 v[98:99], v[98:99], v[98:99] op_sel_hi:[0,1]
	v_pk_add_f32 v[92:93], v[92:93], v[92:93] op_sel_hi:[0,1]
	v_lshlrev_b32_e32 v4, 16, v15
	v_and_b32_e32 v14, 0xffff0000, v15
	v_mov_b32_e32 v5, v99
	v_mov_b32_e32 v15, v93
	v_pk_add_f32 v[92:93], v[4:5], v[14:15]
	s_nop 0
	v_pk_add_f32 v[92:93], v[100:101], v[92:93]
	s_nop 0
	v_add_f32_e32 v3, v92, v93
	s_nop 1
	v_add_f32_dpp v3, v3, v3 quad_perm:[1,0,3,2] row_mask:0xf bank_mask:0xf
	s_nop 1
	v_add_f32_dpp v3, v3, v3 quad_perm:[2,3,0,1] row_mask:0xf bank_mask:0xf
	s_nop 1
	v_add_f32_dpp v3, v3, v3 row_half_mirror row_mask:0xf bank_mask:0xf
	s_nop 1
	v_add_f32_dpp v3, v3, v3 row_mirror row_mask:0xf bank_mask:0xf
	s_nop 1
	v_add_f32_dpp v3, v3, v3 row_bcast:15 row_mask:0xa bank_mask:0xf
	s_nop 0
	v_readlane_b32 s86, v3, 31
	v_readlane_b32 s87, v3, 63
	s_nop 1
	v_mov_b32_e32 v3, s86
	v_add_f32_e32 v3, s87, v3
	v_fmac_f32_e32 v91, 0xba000000, v3
	v_fmac_f32_e32 v87, 0xba000000, v3
	v_fmac_f32_e32 v90, 0xba000000, v3
	v_fmac_f32_e32 v86, 0xba000000, v3
	v_fmac_f32_e32 v8, 0xba000000, v3
	v_fmac_f32_e32 v9, 0xba000000, v3
	v_fmac_f32_e32 v11, 0xba000000, v3
	v_fmac_f32_e32 v89, 0xba000000, v3
	v_fmac_f32_e32 v85, 0xba000000, v3
	v_fmac_f32_e32 v88, 0xba000000, v3
	v_fmac_f32_e32 v84, 0xba000000, v3
	v_fmac_f32_e32 v10, 0xba000000, v3
	v_mov_b32_e32 v96, v87
	v_mov_b32_e32 v97, v86
	v_mov_b32_e32 v102, v91
	v_mov_b32_e32 v103, v90
	v_mov_b32_e32 v104, v11
	v_mov_b32_e32 v105, v9
	v_mov_b32_e32 v11, v8
	v_mov_b32_e32 v94, v85
	v_mov_b32_e32 v95, v84
	v_mov_b32_e32 v100, v89
	v_mov_b32_e32 v101, v88
	v_pk_mul_f32 v[96:97], v[96:97], v[96:97]
	v_pk_mul_f32 v[102:103], v[102:103], v[102:103]
	v_pk_mul_f32 v[112:113], v[104:105], v[104:105]
	v_pk_mul_f32 v[114:115], v[10:11], v[10:11]
	v_fmac_f32_e32 v80, 0xba000000, v3
	v_fmac_f32_e32 v82, 0xba000000, v3
	v_pk_fma_f32 v[94:95], v[94:95], v[94:95], v[96:97]
	v_pk_fma_f32 v[96:97], v[100:101], v[100:101], v[102:103]
	v_pk_mov_b32 v[100:101], v[114:115], v[112:113] op_sel:[1,0]
	v_mov_b32_e32 v115, v113
	v_fmac_f32_e32 v81, 0xba000000, v3
	v_fmac_f32_e32 v83, 0xba000000, v3
	v_fmac_f32_e32 v6, 0xba000000, v3
	v_fmac_f32_e32 v7, 0xba000000, v3
	v_fmac_f32_e32 v1, 0xba000000, v3
	v_mul_f32_e32 v8, v80, v80
	v_mul_f32_e32 v106, v82, v82
	v_pk_add_f32 v[94:95], v[94:95], v[96:97]
	v_pk_add_f32 v[96:97], v[100:101], v[114:115]
	v_fmac_f32_e32 v62, 0xba000000, v3
	v_fmac_f32_e32 v58, 0xba000000, v3
	v_fmac_f32_e32 v60, 0xba000000, v3
	v_fmac_f32_e32 v56, 0xba000000, v3
	v_fmac_f32_e32 v0, 0xba000000, v3
	v_mov_b32_e32 v108, v1
	v_mov_b32_e32 v109, v7
	v_mov_b32_e32 v1, v6
	v_pk_fma_f32 v[8:9], v[80:81], v[80:81], v[8:9] op_sel_hi:[1,1,0]
	v_pk_fma_f32 v[106:107], v[82:83], v[82:83], v[106:107] op_sel_hi:[1,1,0]
	v_pk_add_f32 v[94:95], v[94:95], v[94:95] op_sel_hi:[0,1]
	v_pk_add_f32 v[96:97], v[96:97], v[96:97] op_sel_hi:[0,1]
	v_pk_mul_f32 v[116:117], v[108:109], v[108:109]
	v_pk_mul_f32 v[118:119], v[0:1], v[0:1]
	v_mul_f32_e32 v8, v56, v56
	v_mul_f32_e32 v106, v60, v60
	v_mul_f32_e32 v96, v58, v58
	v_mul_f32_e32 v94, v62, v62
	v_fmac_f32_e32 v52, 0xba000000, v3
	v_fmac_f32_e32 v54, 0xba000000, v3
	v_pk_mov_b32 v[102:103], v[118:119], v[116:117] op_sel:[1,0]
	v_mov_b32_e32 v119, v117
	v_pk_add_f32 v[8:9], v[8:9], v[106:107]
	v_pk_add_f32 v[94:95], v[96:97], v[94:95]
	v_fmac_f32_e32 v53, 0xba000000, v3
	v_fmac_f32_e32 v55, 0xba000000, v3
	v_mul_f32_e32 v6, v52, v52
	v_mul_f32_e32 v110, v54, v54
	v_pk_add_f32 v[100:101], v[102:103], v[118:119]
	v_pk_add_f32 v[8:9], v[8:9], v[94:95]
	v_fmac_f32_e32 v14, 0xba000000, v3
	v_fmac_f32_e32 v4, 0xba000000, v3
	v_fmac_f32_e32 v12, 0xba000000, v3
	v_fmac_f32_e32 v2, 0xba000000, v3
	v_pk_fma_f32 v[6:7], v[52:53], v[52:53], v[6:7] op_sel_hi:[1,1,0]
	v_pk_fma_f32 v[110:111], v[54:55], v[54:55], v[110:111] op_sel_hi:[1,1,0]
	v_pk_add_f32 v[100:101], v[100:101], v[100:101] op_sel_hi:[0,1]
	v_pk_add_f32 v[8:9], v[8:9], v[8:9] op_sel_hi:[0,1]
	v_mul_f32_e32 v6, v2, v2
	v_mul_f32_e32 v110, v12, v12
	v_mul_f32_e32 v100, v4, v4
	v_mul_f32_e32 v8, v14, v14
	v_pk_add_f32 v[6:7], v[6:7], v[110:111]
	v_pk_add_f32 v[8:9], v[100:101], v[8:9]
	v_mov_b32_e32 v92, v85
	v_pk_add_f32 v[6:7], v[6:7], v[8:9]
	v_mov_b32_e32 v93, v87
	v_add_f32_e32 v3, v6, v7
	ds_bpermute_b32 v5, v64, v3
	v_mov_b32_e32 v98, v89
	v_mov_b32_e32 v99, v91
	v_mov_b32_e32 v85, v86
	v_mov_b32_e32 v89, v90
	s_waitcnt lgkmcnt(0)
	v_add_f32_e32 v3, v3, v5
	ds_bpermute_b32 v5, v65, v3
	v_mov_b32_e32 v59, v62
	v_mov_b32_e32 v57, v60
	s_waitcnt lgkmcnt(0)
	v_add_f32_e32 v3, v3, v5
	ds_bpermute_b32 v5, v66, v3
	s_waitcnt lgkmcnt(0)
	v_add_f32_e32 v3, v3, v5
	ds_bpermute_b32 v5, v67, v3
	s_waitcnt lgkmcnt(0)
	v_add_f32_e32 v3, v3, v5
	ds_bpermute_b32 v5, v68, v3
	s_waitcnt lgkmcnt(0)
	v_add_f32_e32 v3, v3, v5
	ds_bpermute_b32 v5, v69, v3
	s_waitcnt lgkmcnt(0)
	v_add_f32_e32 v3, v3, v5
	v_fmamk_f32 v3, v3, 0x3a000000, v70
	v_mul_f32_e32 v5, 0x4f800000, v3
	v_cmp_gt_f32_e32 vcc, s3, v3
	s_nop 1
	v_cndmask_b32_e32 v3, v3, v5, vcc
	v_sqrt_f32_e32 v5, v3
	s_nop 0
	v_add_u32_e32 v6, -1, v5
	v_add_u32_e32 v7, 1, v5
	v_fma_f32 v8, -v6, v5, v3
	v_fma_f32 v9, -v7, v5, v3
	v_cmp_ge_f32_e64 s[0:1], 0, v8
	s_nop 1
	v_cndmask_b32_e64 v5, v5, v6, s[0:1]
	v_cmp_lt_f32_e64 s[0:1], 0, v9
	s_nop 1
	v_cndmask_b32_e64 v5, v5, v7, s[0:1]
	v_mul_f32_e32 v6, 0x37800000, v5
	v_cndmask_b32_e32 v5, v5, v6, vcc
	v_cmp_class_f32_e32 vcc, v3, v71
	s_nop 1
	v_cndmask_b32_e32 v3, v5, v3, vcc
	v_div_scale_f32 v5, s[0:1], v3, v3, 1.0
	v_rcp_f32_e32 v7, v5
	v_div_scale_f32 v6, vcc, 1.0, v3, 1.0
	v_fma_f32 v8, -v5, v7, 1.0
	v_fmac_f32_e32 v7, v8, v7
	v_mul_f32_e32 v8, v6, v7
	v_fma_f32 v9, -v5, v8, v6
	v_fmac_f32_e32 v8, v9, v7
	v_fma_f32 v5, -v5, v8, v6
	v_div_fmas_f32 v5, v5, v7, v8
	v_div_fixup_f32 v94, v5, v3, 1.0
	v_pk_mul_f32 v[6:7], v[92:93], v[94:95] op_sel_hi:[1,0]
	v_pk_mul_f32 v[8:9], v[98:99], v[94:95] op_sel_hi:[1,0]
	v_pk_fma_f32 v[6:7], v[72:73], v[6:7], v[76:77]
	v_pk_fma_f32 v[8:9], v[74:75], v[8:9], v[78:79]
	global_store_dwordx4 v[50:51], v[6:9], off offset:-4096
	s_nop 0
	v_pk_mul_f32 v[76:77], v[88:89], v[94:95] op_sel_hi:[1,0]
	v_pk_mul_f32 v[78:79], v[84:85], v[94:95] op_sel_hi:[1,0]
	v_pk_mul_f32 v[10:11], v[10:11], v[94:95] op_sel_hi:[1,0]
	v_pk_mul_f32 v[56:57], v[56:57], v[94:95] op_sel_hi:[1,0]
	v_pk_mul_f32 v[0:1], v[0:1], v[94:95] op_sel_hi:[1,0]
	v_mov_b32_e32 v5, v14
	v_mov_b32_e32 v3, v12
	v_pk_mul_f32 v[4:5], v[4:5], v[94:95] op_sel_hi:[1,0]
	v_cmp_lt_i32_e32 vcc, s10, v148
	s_or_b64 s[8:9], vcc, s[8:9]
	s_waitcnt vmcnt(13)
	v_pk_fma_f32 v[6:7], v[170:171], v[78:79], v[174:175]
	v_pk_fma_f32 v[8:9], v[172:173], v[76:77], v[176:177]
	global_store_dwordx4 v[50:51], v[6:9], off offset:-4080
	s_nop 0
	v_pk_mul_f32 v[76:77], v[104:105], v[94:95] op_sel_hi:[1,0]
	s_waitcnt vmcnt(12)
	v_pk_fma_f32 v[6:7], v[178:179], v[10:11], v[182:183]
	v_pk_fma_f32 v[8:9], v[180:181], v[76:77], v[184:185]
	global_store_dwordx4 v[50:51], v[6:9], off offset:-2048
	s_nop 0
	v_pk_mul_f32 v[10:11], v[82:83], v[94:95] op_sel_hi:[1,0]
	v_pk_mul_f32 v[76:77], v[80:81], v[94:95] op_sel_hi:[1,0]
	s_waitcnt vmcnt(11)
	v_pk_fma_f32 v[8:9], v[188:189], v[10:11], v[192:193]
	v_pk_fma_f32 v[6:7], v[186:187], v[76:77], v[190:191]
	global_store_dwordx4 v[50:51], v[6:9], off offset:-2032
	s_nop 0
	v_pk_mul_f32 v[10:11], v[58:59], v[94:95] op_sel_hi:[1,0]
	s_waitcnt vmcnt(10)
	v_pk_fma_f32 v[6:7], v[194:195], v[56:57], v[198:199]
	v_pk_fma_f32 v[8:9], v[196:197], v[10:11], v[200:201]
	global_store_dwordx4 v[50:51], v[6:9], off
	s_nop 0
	v_pk_mul_f32 v[10:11], v[108:109], v[94:95] op_sel_hi:[1,0]
	s_waitcnt vmcnt(9)
	v_pk_fma_f32 v[6:7], v[202:203], v[0:1], v[206:207]
	v_pk_fma_f32 v[8:9], v[204:205], v[10:11], v[208:209]
	global_store_dwordx4 v[50:51], v[6:9], off offset:16
	s_nop 0
	v_pk_mul_f32 v[0:1], v[54:55], v[94:95] op_sel_hi:[1,0]
	v_pk_mul_f32 v[10:11], v[52:53], v[94:95] op_sel_hi:[1,0]
	s_waitcnt vmcnt(8)
	v_pk_fma_f32 v[8:9], v[212:213], v[0:1], v[216:217]
	v_pk_fma_f32 v[6:7], v[210:211], v[10:11], v[214:215]
	global_store_dwordx4 v[50:51], v[6:9], off offset:2048
	s_nop 0
	v_pk_mul_f32 v[0:1], v[2:3], v[94:95] op_sel_hi:[1,0]
	s_waitcnt vmcnt(7)
	v_pk_fma_f32 v[2:3], v[220:221], v[4:5], v[224:225]
	v_pk_fma_f32 v[0:1], v[218:219], v[0:1], v[222:223]
	global_store_dwordx4 v[50:51], v[0:3], off offset:2064
	v_lshl_add_u64 v[50:51], v[50:51], 0, s[6:7]
	s_andn2_b64 exec, exec, s[8:9]
	s_cbranch_execnz .LBB0_2681
